# grid barrier poll back-off: 6 polls at s_sleep 8, then s_sleep 48
# speedup vs baseline: 1.0035x; 1.0035x over previous
.Lgb_poll:
	global_load_dword v1, v2, s[4:5] offset:544 sc1
	s_waitcnt vmcnt(0)
	v_cmp_le_u32_e32 vcc, s12, v1
	s_cbranch_vccnz .Lgb_acq
	s_mov_b32 s3, 0
.Lgb_spin:
	s_sleep 8
	global_load_dword v1, v2, s[4:5] offset:544 sc1
	s_add_i32 s3, s3, 1
	s_waitcnt vmcnt(0)
	v_cmp_gt_u32_e32 vcc, s12, v1
	s_cbranch_vccz .Lgb_acq
	s_cmp_lt_u32 s3, 6
	s_cbranch_scc1 .Lgb_spin
.Lgb_spin2:
	s_sleep 48
	global_load_dword v1, v2, s[4:5] offset:544 sc1
	s_waitcnt vmcnt(0)
	v_cmp_gt_u32_e32 vcc, s12, v1
	s_cbranch_vccnz .Lgb_spin2
